# replace 26 cg grid.sync with flag-gather barrier in d_ws (master block polls 16-bit arrival flags, 8 release words)
# speedup vs baseline: 1.2058x; 1.2058x over previous
.LBB0_189:
	s_cmp_gt_i32 s17, 1
	s_cselect_b64 s[0:1], -1, 0
	s_and_b64 s[4:5], s[18:19], s[0:1]
	s_andn2_b64 vcc, exec, s[4:5]
	v_lshrrev_b32_e32 v200, 20, v0
	v_lshrrev_b32_e32 v201, 10, v0
	s_cbranch_vccnz .LBB0_201
	s_waitcnt vmcnt(0)
	v_or_b32_e32 v0, v201, v200
	s_movk_i32 s3, 0x3ff
	v_and_or_b32 v0, v0, s3, v199
	v_cmp_eq_u32_e32 vcc, 0, v0
	s_barrier
	s_and_saveexec_b64 s[4:5], vcc
	s_cbranch_execz .LBB0_200
	buffer_wbl2 sc1
	s_waitcnt vmcnt(0)
	s_add_u32 s6, s14, 0x5be8c00
	s_addc_u32 s7, s15, 0
	s_lshl_b32 s3, s2, 1
	v_mov_b32_e32 v0, s3
	v_mov_b32_e32 v1, 0x9301
	global_store_short v0, v1, s[6:7] sc1
	s_cmp_lg_u32 s2, 0
	s_cbranch_scc1 .Lgbar_wait_0
	s_lshr_b32 s3, s33, 3
	s_bfm_b64 s[8:9], s3, 0
	s_cmpk_gt_u32 s33, 0x1ff
	s_cselect_b64 s[8:9], -1, s[8:9]
	s_mov_b64 exec, -1
	v_mbcnt_lo_u32_b32 v229, -1, 0
	v_mbcnt_hi_u32_b32 v229, -1, v229
	v_lshlrev_b32_e32 v229, 4, v229
	s_mov_b32 s10, 0x93019301
	s_mov_b64 exec, s[8:9]
.Lgbar_poll_0:
	global_load_dwordx4 v[0:3], v229, s[6:7] sc1
	s_waitcnt vmcnt(0)
	v_xor_b32_e32 v0, s10, v0
	v_xor_b32_e32 v1, s10, v1
	v_xor_b32_e32 v2, s10, v2
	v_xor_b32_e32 v3, s10, v3
	v_or3_b32 v0, v0, v1, v2
	v_or_b32_e32 v0, v0, v3
	v_cmp_eq_u32_e32 vcc, 0, v0
	s_cmp_eq_u64 vcc, exec
	s_cbranch_scc1 .Lgbar_rel_0
	s_sleep 1
	s_branch .Lgbar_poll_0
.Lgbar_rel_0:
	s_mov_b64 exec, -1
	v_lshlrev_b32_e32 v0, 4, v229
	v_mov_b32_e32 v1, 0x93a70001
	s_mov_b32 exec_lo, 0xff
	s_mov_b32 exec_hi, 0
	global_store_dword v0, v1, s[6:7] offset:1024 sc1
	s_mov_b64 exec, 1
.Lgbar_wait_0:
	s_and_b32 s3, s2, 7
	s_lshl_b32 s3, s3, 8
	s_add_u32 s6, s6, s3
	s_addc_u32 s7, s7, 0
	v_mov_b32_e32 v0, 0
.Lgbar_spin_0:
	global_load_dword v1, v0, s[6:7] offset:1024 sc1
	s_waitcnt vmcnt(0)
	v_cmp_eq_u32_e32 vcc, 0x93a70001, v1
	s_cbranch_vccnz .Lgbar_done_0
	s_sleep 1
	s_branch .Lgbar_spin_0
.Lgbar_done_0:
	buffer_inv sc1
	s_waitcnt vmcnt(0)

.LBB0_241:
	s_cmp_gt_i32 s17, 2
	s_cselect_b64 s[0:1], -1, 0
	s_and_b64 s[4:5], s[8:9], s[0:1]
	s_andn2_b64 vcc, exec, s[4:5]
	s_cbranch_vccnz .LBB0_253
	s_waitcnt vmcnt(0)
	v_or_b32_e32 v0, v201, v200
	s_movk_i32 s3, 0x3ff
	v_and_or_b32 v0, v0, s3, v199
	v_cmp_eq_u32_e32 vcc, 0, v0
	s_waitcnt lgkmcnt(0)
	s_barrier
	s_and_saveexec_b64 s[4:5], vcc
	s_cbranch_execz .LBB0_252
	buffer_wbl2 sc1
	s_waitcnt vmcnt(0)
	s_add_u32 s6, s14, 0x5be8c00
	s_addc_u32 s7, s15, 0
	s_lshl_b32 s3, s2, 1
	v_mov_b32_e32 v0, s3
	v_mov_b32_e32 v1, 0x9302
	global_store_short v0, v1, s[6:7] sc1
	s_cmp_lg_u32 s2, 0
	s_cbranch_scc1 .Lgbar_wait_1
	s_lshr_b32 s3, s33, 3
	s_bfm_b64 s[8:9], s3, 0
	s_cmpk_gt_u32 s33, 0x1ff
	s_cselect_b64 s[8:9], -1, s[8:9]
	s_mov_b64 exec, -1
	v_mbcnt_lo_u32_b32 v229, -1, 0
	v_mbcnt_hi_u32_b32 v229, -1, v229
	v_lshlrev_b32_e32 v229, 4, v229
	s_mov_b32 s10, 0x93029302
	s_mov_b64 exec, s[8:9]

.Lgbar_rel_1:
	s_mov_b64 exec, -1
	v_lshlrev_b32_e32 v0, 4, v229
	v_mov_b32_e32 v1, 0x93a70002
	s_mov_b32 exec_lo, 0xff
	s_mov_b32 exec_hi, 0
	global_store_dword v0, v1, s[6:7] offset:1024 sc1
	s_mov_b64 exec, 1

.Lgbar_spin_1:
	global_load_dword v1, v0, s[6:7] offset:1024 sc1
	s_waitcnt vmcnt(0)
	v_cmp_eq_u32_e32 vcc, 0x93a70002, v1
	s_cbranch_vccnz .Lgbar_done_1
	s_sleep 1
	s_branch .Lgbar_spin_1

.LBB0_538:
	s_cmp_gt_i32 s17, 3
	s_cselect_b64 s[4:5], -1, 0
	s_and_b64 s[0:1], s[6:7], s[4:5]
	s_andn2_b64 vcc, exec, s[0:1]
	s_cbranch_vccnz .LBB0_550
	s_waitcnt vmcnt(0)
	v_or_b32_e32 v0, v201, v200
	s_movk_i32 s0, 0x3ff
	v_and_or_b32 v0, v0, s0, v199
	v_cmp_eq_u32_e32 vcc, 0, v0
	s_waitcnt lgkmcnt(0)
	s_barrier
	s_and_saveexec_b64 s[0:1], vcc
	s_cbranch_execz .LBB0_549
	buffer_wbl2 sc1
	s_waitcnt vmcnt(0)
	s_add_u32 s6, s14, 0x5be8c00
	s_addc_u32 s7, s15, 0
	s_lshl_b32 s3, s2, 1
	v_mov_b32_e32 v0, s3
	v_mov_b32_e32 v1, 0x9303
	global_store_short v0, v1, s[6:7] sc1
	s_cmp_lg_u32 s2, 0
	s_cbranch_scc1 .Lgbar_wait_2
	s_lshr_b32 s3, s33, 3
	s_bfm_b64 s[8:9], s3, 0
	s_cmpk_gt_u32 s33, 0x1ff
	s_cselect_b64 s[8:9], -1, s[8:9]
	s_mov_b64 exec, -1
	v_mbcnt_lo_u32_b32 v229, -1, 0
	v_mbcnt_hi_u32_b32 v229, -1, v229
	v_lshlrev_b32_e32 v229, 4, v229
	s_mov_b32 s10, 0x93039303
	s_mov_b64 exec, s[8:9]

.Lgbar_rel_2:
	s_mov_b64 exec, -1
	v_lshlrev_b32_e32 v0, 4, v229
	v_mov_b32_e32 v1, 0x93a70003
	s_mov_b32 exec_lo, 0xff
	s_mov_b32 exec_hi, 0
	global_store_dword v0, v1, s[6:7] offset:1024 sc1
	s_mov_b64 exec, 1

.Lgbar_spin_2:
	global_load_dword v1, v0, s[6:7] offset:1024 sc1
	s_waitcnt vmcnt(0)
	v_cmp_eq_u32_e32 vcc, 0x93a70003, v1
	s_cbranch_vccnz .Lgbar_done_2
	s_sleep 1
	s_branch .Lgbar_spin_2

.LBB0_560:
	s_cmp_gt_i32 s17, 4
	s_cselect_b64 s[6:7], -1, 0
	s_and_b64 s[0:1], s[0:1], s[6:7]
	s_andn2_b64 vcc, exec, s[0:1]
	s_cbranch_vccnz .LBB0_572
	s_waitcnt vmcnt(0)
	v_or_b32_e32 v0, v201, v200
	s_movk_i32 s0, 0x3ff
	v_and_or_b32 v0, v0, s0, v199
	v_cmp_eq_u32_e32 vcc, 0, v0
	s_waitcnt lgkmcnt(0)
	s_barrier
	s_and_saveexec_b64 s[0:1], vcc
	s_cbranch_execz .LBB0_571
	buffer_wbl2 sc1
	s_waitcnt vmcnt(0)
	s_add_u32 s4, s14, 0x5be8c00
	s_addc_u32 s5, s15, 0
	s_lshl_b32 s3, s2, 1
	v_mov_b32_e32 v0, s3
	v_mov_b32_e32 v1, 0x9304
	global_store_short v0, v1, s[4:5] sc1
	s_cmp_lg_u32 s2, 0
	s_cbranch_scc1 .Lgbar_wait_3
	s_lshr_b32 s3, s33, 3
	s_bfm_b64 s[8:9], s3, 0
	s_cmpk_gt_u32 s33, 0x1ff
	s_cselect_b64 s[8:9], -1, s[8:9]
	s_mov_b64 exec, -1
	v_mbcnt_lo_u32_b32 v229, -1, 0
	v_mbcnt_hi_u32_b32 v229, -1, v229
	v_lshlrev_b32_e32 v229, 4, v229
	s_mov_b32 s10, 0x93049304
	s_mov_b64 exec, s[8:9]
.Lgbar_poll_3:
	global_load_dwordx4 v[0:3], v229, s[4:5] sc1
	s_waitcnt vmcnt(0)
	v_xor_b32_e32 v0, s10, v0
	v_xor_b32_e32 v1, s10, v1
	v_xor_b32_e32 v2, s10, v2
	v_xor_b32_e32 v3, s10, v3
	v_or3_b32 v0, v0, v1, v2
	v_or_b32_e32 v0, v0, v3
	v_cmp_eq_u32_e32 vcc, 0, v0
	s_cmp_eq_u64 vcc, exec
	s_cbranch_scc1 .Lgbar_rel_3
	s_sleep 1
	s_branch .Lgbar_poll_3
.Lgbar_rel_3:
	s_mov_b64 exec, -1
	v_lshlrev_b32_e32 v0, 4, v229
	v_mov_b32_e32 v1, 0x93a70004
	s_mov_b32 exec_lo, 0xff
	s_mov_b32 exec_hi, 0
	global_store_dword v0, v1, s[4:5] offset:1024 sc1
	s_mov_b64 exec, 1
.Lgbar_wait_3:
	s_and_b32 s3, s2, 7
	s_lshl_b32 s3, s3, 8
	s_add_u32 s4, s4, s3
	s_addc_u32 s5, s5, 0
	v_mov_b32_e32 v0, 0
.Lgbar_spin_3:
	global_load_dword v1, v0, s[4:5] offset:1024 sc1
	s_waitcnt vmcnt(0)
	v_cmp_eq_u32_e32 vcc, 0x93a70004, v1
	s_cbranch_vccnz .Lgbar_done_3
	s_sleep 1
	s_branch .Lgbar_spin_3

.LBB0_655:
	s_cmp_gt_i32 s17, 5
	s_cselect_b64 s[6:7], -1, 0
	s_and_b64 s[0:1], s[4:5], s[6:7]
	s_andn2_b64 vcc, exec, s[0:1]
	s_cbranch_vccnz .LBB0_667
	s_waitcnt vmcnt(0)
	v_or_b32_e32 v0, v201, v200
	s_movk_i32 s0, 0x3ff
	v_and_or_b32 v0, v0, s0, v199
	v_cmp_eq_u32_e32 vcc, 0, v0
	s_waitcnt lgkmcnt(0)
	s_barrier
	s_and_saveexec_b64 s[0:1], vcc
	s_cbranch_execz .LBB0_666
	buffer_wbl2 sc1
	s_waitcnt vmcnt(0)
	s_add_u32 s4, s14, 0x5be8c00
	s_addc_u32 s5, s15, 0
	s_lshl_b32 s3, s2, 1
	v_mov_b32_e32 v0, s3
	v_mov_b32_e32 v1, 0x9305
	global_store_short v0, v1, s[4:5] sc1
	s_cmp_lg_u32 s2, 0
	s_cbranch_scc1 .Lgbar_wait_4
	s_lshr_b32 s3, s33, 3
	s_bfm_b64 s[8:9], s3, 0
	s_cmpk_gt_u32 s33, 0x1ff
	s_cselect_b64 s[8:9], -1, s[8:9]
	s_mov_b64 exec, -1
	v_mbcnt_lo_u32_b32 v229, -1, 0
	v_mbcnt_hi_u32_b32 v229, -1, v229
	v_lshlrev_b32_e32 v229, 4, v229
	s_mov_b32 s10, 0x93059305
	s_mov_b64 exec, s[8:9]

.Lgbar_rel_4:
	s_mov_b64 exec, -1
	v_lshlrev_b32_e32 v0, 4, v229
	v_mov_b32_e32 v1, 0x93a70005
	s_mov_b32 exec_lo, 0xff
	s_mov_b32 exec_hi, 0
	global_store_dword v0, v1, s[4:5] offset:1024 sc1
	s_mov_b64 exec, 1

.Lgbar_spin_4:
	global_load_dword v1, v0, s[4:5] offset:1024 sc1
	s_waitcnt vmcnt(0)
	v_cmp_eq_u32_e32 vcc, 0x93a70005, v1
	s_cbranch_vccnz .Lgbar_done_4
	s_sleep 1
	s_branch .Lgbar_spin_4

.LBB0_687:
	s_cmp_gt_i32 s17, 6
	s_cselect_b64 s[6:7], -1, 0
	s_and_b64 s[0:1], s[0:1], s[6:7]
	s_andn2_b64 vcc, exec, s[0:1]
	s_cbranch_vccnz .LBB0_699
	s_waitcnt vmcnt(0)
	v_or_b32_e32 v0, v201, v200
	s_movk_i32 s0, 0x3ff
	v_and_or_b32 v0, v0, s0, v199
	v_cmp_eq_u32_e32 vcc, 0, v0
	s_waitcnt lgkmcnt(0)
	s_barrier
	s_and_saveexec_b64 s[0:1], vcc
	s_cbranch_execz .LBB0_698
	buffer_wbl2 sc1
	s_waitcnt vmcnt(0)
	s_add_u32 s4, s14, 0x5be8c00
	s_addc_u32 s5, s15, 0
	s_lshl_b32 s3, s2, 1
	v_mov_b32_e32 v0, s3
	v_mov_b32_e32 v1, 0x9306
	global_store_short v0, v1, s[4:5] sc1
	s_cmp_lg_u32 s2, 0
	s_cbranch_scc1 .Lgbar_wait_5
	s_lshr_b32 s3, s33, 3
	s_bfm_b64 s[8:9], s3, 0
	s_cmpk_gt_u32 s33, 0x1ff
	s_cselect_b64 s[8:9], -1, s[8:9]
	s_mov_b64 exec, -1
	v_mbcnt_lo_u32_b32 v229, -1, 0
	v_mbcnt_hi_u32_b32 v229, -1, v229
	v_lshlrev_b32_e32 v229, 4, v229
	s_mov_b32 s10, 0x93069306
	s_mov_b64 exec, s[8:9]

.Lgbar_rel_5:
	s_mov_b64 exec, -1
	v_lshlrev_b32_e32 v0, 4, v229
	v_mov_b32_e32 v1, 0x93a70006
	s_mov_b32 exec_lo, 0xff
	s_mov_b32 exec_hi, 0
	global_store_dword v0, v1, s[4:5] offset:1024 sc1
	s_mov_b64 exec, 1

.Lgbar_spin_5:
	global_load_dword v1, v0, s[4:5] offset:1024 sc1
	s_waitcnt vmcnt(0)
	v_cmp_eq_u32_e32 vcc, 0x93a70006, v1
	s_cbranch_vccnz .Lgbar_done_5
	s_sleep 1
	s_branch .Lgbar_spin_5

.LBB0_739:
	s_cmp_gt_i32 s17, 7
	s_cselect_b64 s[6:7], -1, 0
	s_and_b64 s[0:1], s[4:5], s[6:7]
	s_andn2_b64 vcc, exec, s[0:1]
	s_cbranch_vccnz .LBB0_751
	s_waitcnt vmcnt(0)
	v_or_b32_e32 v0, v201, v200
	s_movk_i32 s0, 0x3ff
	v_and_or_b32 v0, v0, s0, v199
	v_cmp_eq_u32_e32 vcc, 0, v0
	s_waitcnt lgkmcnt(0)
	s_barrier
	s_and_saveexec_b64 s[0:1], vcc
	s_cbranch_execz .LBB0_750
	buffer_wbl2 sc1
	s_waitcnt vmcnt(0)
	s_add_u32 s4, s14, 0x5be8c00
	s_addc_u32 s5, s15, 0
	s_lshl_b32 s3, s2, 1
	v_mov_b32_e32 v0, s3
	v_mov_b32_e32 v1, 0x9307
	global_store_short v0, v1, s[4:5] sc1
	s_cmp_lg_u32 s2, 0
	s_cbranch_scc1 .Lgbar_wait_6
	s_lshr_b32 s3, s33, 3
	s_bfm_b64 s[8:9], s3, 0
	s_cmpk_gt_u32 s33, 0x1ff
	s_cselect_b64 s[8:9], -1, s[8:9]
	s_mov_b64 exec, -1
	v_mbcnt_lo_u32_b32 v229, -1, 0
	v_mbcnt_hi_u32_b32 v229, -1, v229
	v_lshlrev_b32_e32 v229, 4, v229
	s_mov_b32 s10, 0x93079307
	s_mov_b64 exec, s[8:9]

.Lgbar_rel_6:
	s_mov_b64 exec, -1
	v_lshlrev_b32_e32 v0, 4, v229
	v_mov_b32_e32 v1, 0x93a70007
	s_mov_b32 exec_lo, 0xff
	s_mov_b32 exec_hi, 0
	global_store_dword v0, v1, s[4:5] offset:1024 sc1
	s_mov_b64 exec, 1

.Lgbar_spin_6:
	global_load_dword v1, v0, s[4:5] offset:1024 sc1
	s_waitcnt vmcnt(0)
	v_cmp_eq_u32_e32 vcc, 0x93a70007, v1
	s_cbranch_vccnz .Lgbar_done_6
	s_sleep 1
	s_branch .Lgbar_spin_6

.LBB0_759:
	s_cmp_gt_i32 s17, 8
	s_cselect_b64 s[6:7], -1, 0
	s_and_b64 s[0:1], s[0:1], s[6:7]
	s_andn2_b64 vcc, exec, s[0:1]
	s_cbranch_vccnz .LBB0_771
	s_waitcnt vmcnt(0)
	v_or_b32_e32 v0, v201, v200
	s_movk_i32 s0, 0x3ff
	v_and_or_b32 v0, v0, s0, v199
	v_cmp_eq_u32_e32 vcc, 0, v0
	s_waitcnt lgkmcnt(0)
	s_barrier
	s_and_saveexec_b64 s[0:1], vcc
	s_cbranch_execz .LBB0_770
	buffer_wbl2 sc1
	s_waitcnt vmcnt(0)
	s_add_u32 s4, s14, 0x5be8c00
	s_addc_u32 s5, s15, 0
	s_lshl_b32 s3, s2, 1
	v_mov_b32_e32 v0, s3
	v_mov_b32_e32 v1, 0x9308
	global_store_short v0, v1, s[4:5] sc1
	s_cmp_lg_u32 s2, 0
	s_cbranch_scc1 .Lgbar_wait_7
	s_lshr_b32 s3, s33, 3
	s_bfm_b64 s[8:9], s3, 0
	s_cmpk_gt_u32 s33, 0x1ff
	s_cselect_b64 s[8:9], -1, s[8:9]
	s_mov_b64 exec, -1
	v_mbcnt_lo_u32_b32 v229, -1, 0
	v_mbcnt_hi_u32_b32 v229, -1, v229
	v_lshlrev_b32_e32 v229, 4, v229
	s_mov_b32 s10, 0x93089308
	s_mov_b64 exec, s[8:9]

.Lgbar_rel_7:
	s_mov_b64 exec, -1
	v_lshlrev_b32_e32 v0, 4, v229
	v_mov_b32_e32 v1, 0x93a70008
	s_mov_b32 exec_lo, 0xff
	s_mov_b32 exec_hi, 0
	global_store_dword v0, v1, s[4:5] offset:1024 sc1
	s_mov_b64 exec, 1

.Lgbar_spin_7:
	global_load_dword v1, v0, s[4:5] offset:1024 sc1
	s_waitcnt vmcnt(0)
	v_cmp_eq_u32_e32 vcc, 0x93a70008, v1
	s_cbranch_vccnz .Lgbar_done_7
	s_sleep 1
	s_branch .Lgbar_spin_7

.LBB0_811:
	s_cmp_gt_i32 s17, 9
	s_cselect_b64 s[0:1], -1, 0
	s_and_b64 s[4:5], s[4:5], s[0:1]
	s_andn2_b64 vcc, exec, s[4:5]
	s_cbranch_vccnz .LBB0_823
	s_waitcnt vmcnt(0)
	v_or_b32_e32 v0, v201, v200
	s_movk_i32 s3, 0x3ff
	v_and_or_b32 v0, v0, s3, v199
	v_cmp_eq_u32_e32 vcc, 0, v0
	s_waitcnt lgkmcnt(0)
	s_barrier
	s_and_saveexec_b64 s[4:5], vcc
	s_cbranch_execz .LBB0_822
	buffer_wbl2 sc1
	s_waitcnt vmcnt(0)
	s_add_u32 s6, s14, 0x5be8c00
	s_addc_u32 s7, s15, 0
	s_lshl_b32 s3, s2, 1
	v_mov_b32_e32 v0, s3
	v_mov_b32_e32 v1, 0x9309
	global_store_short v0, v1, s[6:7] sc1
	s_cmp_lg_u32 s2, 0
	s_cbranch_scc1 .Lgbar_wait_8
	s_lshr_b32 s3, s33, 3
	s_bfm_b64 s[8:9], s3, 0
	s_cmpk_gt_u32 s33, 0x1ff
	s_cselect_b64 s[8:9], -1, s[8:9]
	s_mov_b64 exec, -1
	v_mbcnt_lo_u32_b32 v229, -1, 0
	v_mbcnt_hi_u32_b32 v229, -1, v229
	v_lshlrev_b32_e32 v229, 4, v229
	s_mov_b32 s10, 0x93099309
	s_mov_b64 exec, s[8:9]

.Lgbar_rel_8:
	s_mov_b64 exec, -1
	v_lshlrev_b32_e32 v0, 4, v229
	v_mov_b32_e32 v1, 0x93a70009
	s_mov_b32 exec_lo, 0xff
	s_mov_b32 exec_hi, 0
	global_store_dword v0, v1, s[6:7] offset:1024 sc1
	s_mov_b64 exec, 1

.Lgbar_spin_8:
	global_load_dword v1, v0, s[6:7] offset:1024 sc1
	s_waitcnt vmcnt(0)
	v_cmp_eq_u32_e32 vcc, 0x93a70009, v1
	s_cbranch_vccnz .Lgbar_done_8
	s_sleep 1
	s_branch .Lgbar_spin_8

.LBB0_991:
	s_cmp_gt_i32 s17, 10
	s_cselect_b64 s[0:1], -1, 0
	s_and_b64 s[4:5], s[6:7], s[0:1]
	s_andn2_b64 vcc, exec, s[4:5]
	s_cbranch_vccnz .LBB0_1003
	s_waitcnt vmcnt(0)
	v_or_b32_e32 v0, v201, v200
	s_movk_i32 s3, 0x3ff
	v_and_or_b32 v0, v0, s3, v199
	v_cmp_eq_u32_e32 vcc, 0, v0
	s_waitcnt lgkmcnt(0)
	s_barrier
	s_and_saveexec_b64 s[4:5], vcc
	s_cbranch_execz .LBB0_1002
	buffer_wbl2 sc1
	s_waitcnt vmcnt(0)
	s_add_u32 s6, s14, 0x5be8c00
	s_addc_u32 s7, s15, 0
	s_lshl_b32 s3, s2, 1
	v_mov_b32_e32 v0, s3
	v_mov_b32_e32 v1, 0x930a
	global_store_short v0, v1, s[6:7] sc1
	s_cmp_lg_u32 s2, 0
	s_cbranch_scc1 .Lgbar_wait_9
	s_lshr_b32 s3, s33, 3
	s_bfm_b64 s[8:9], s3, 0
	s_cmpk_gt_u32 s33, 0x1ff
	s_cselect_b64 s[8:9], -1, s[8:9]
	s_mov_b64 exec, -1
	v_mbcnt_lo_u32_b32 v229, -1, 0
	v_mbcnt_hi_u32_b32 v229, -1, v229
	v_lshlrev_b32_e32 v229, 4, v229
	s_mov_b32 s10, 0x930a930a
	s_mov_b64 exec, s[8:9]

.Lgbar_rel_9:
	s_mov_b64 exec, -1
	v_lshlrev_b32_e32 v0, 4, v229
	v_mov_b32_e32 v1, 0x93a7000a
	s_mov_b32 exec_lo, 0xff
	s_mov_b32 exec_hi, 0
	global_store_dword v0, v1, s[6:7] offset:1024 sc1
	s_mov_b64 exec, 1

.Lgbar_spin_9:
	global_load_dword v1, v0, s[6:7] offset:1024 sc1
	s_waitcnt vmcnt(0)
	v_cmp_eq_u32_e32 vcc, 0x93a7000a, v1
	s_cbranch_vccnz .Lgbar_done_9
	s_sleep 1
	s_branch .Lgbar_spin_9

.LBB0_1030:
	s_cmp_gt_i32 s17, 11
	s_cselect_b64 s[0:1], -1, 0
	s_and_b64 s[4:5], s[4:5], s[0:1]
	s_andn2_b64 vcc, exec, s[4:5]
	s_cbranch_vccnz .LBB0_1042
	s_waitcnt vmcnt(0)
	v_or_b32_e32 v0, v201, v200
	s_movk_i32 s3, 0x3ff
	v_and_or_b32 v0, v0, s3, v199
	v_cmp_eq_u32_e32 vcc, 0, v0
	s_waitcnt lgkmcnt(0)
	s_barrier
	s_and_saveexec_b64 s[4:5], vcc
	s_cbranch_execz .LBB0_1041
	buffer_wbl2 sc1
	s_waitcnt vmcnt(0)
	s_add_u32 s6, s14, 0x5be8c00
	s_addc_u32 s7, s15, 0
	s_lshl_b32 s3, s2, 1
	v_mov_b32_e32 v0, s3
	v_mov_b32_e32 v1, 0x930b
	global_store_short v0, v1, s[6:7] sc1
	s_cmp_lg_u32 s2, 0
	s_cbranch_scc1 .Lgbar_wait_10
	s_lshr_b32 s3, s33, 3
	s_bfm_b64 s[8:9], s3, 0
	s_cmpk_gt_u32 s33, 0x1ff
	s_cselect_b64 s[8:9], -1, s[8:9]
	s_mov_b64 exec, -1
	v_mbcnt_lo_u32_b32 v229, -1, 0
	v_mbcnt_hi_u32_b32 v229, -1, v229
	v_lshlrev_b32_e32 v229, 4, v229
	s_mov_b32 s10, 0x930b930b
	s_mov_b64 exec, s[8:9]

.Lgbar_rel_10:
	s_mov_b64 exec, -1
	v_lshlrev_b32_e32 v0, 4, v229
	v_mov_b32_e32 v1, 0x93a7000b
	s_mov_b32 exec_lo, 0xff
	s_mov_b32 exec_hi, 0
	global_store_dword v0, v1, s[6:7] offset:1024 sc1
	s_mov_b64 exec, 1

.Lgbar_spin_10:
	global_load_dword v1, v0, s[6:7] offset:1024 sc1
	s_waitcnt vmcnt(0)
	v_cmp_eq_u32_e32 vcc, 0x93a7000b, v1
	s_cbranch_vccnz .Lgbar_done_10
	s_sleep 1
	s_branch .Lgbar_spin_10

.LBB0_1082:
	s_cmp_gt_i32 s17, 12
	s_cselect_b64 s[6:7], -1, 0
	s_and_b64 s[0:1], s[4:5], s[6:7]
	s_andn2_b64 vcc, exec, s[0:1]
	s_cbranch_vccnz .LBB0_1094
	s_waitcnt vmcnt(0)
	v_or_b32_e32 v0, v201, v200
	s_movk_i32 s0, 0x3ff
	v_and_or_b32 v0, v0, s0, v199
	v_cmp_eq_u32_e32 vcc, 0, v0
	s_waitcnt lgkmcnt(0)
	s_barrier
	s_and_saveexec_b64 s[0:1], vcc
	s_cbranch_execz .LBB0_1093
	buffer_wbl2 sc1
	s_waitcnt vmcnt(0)
	s_add_u32 s4, s14, 0x5be8c00
	s_addc_u32 s5, s15, 0
	s_lshl_b32 s3, s2, 1
	v_mov_b32_e32 v0, s3
	v_mov_b32_e32 v1, 0x930c
	global_store_short v0, v1, s[4:5] sc1
	s_cmp_lg_u32 s2, 0
	s_cbranch_scc1 .Lgbar_wait_11
	s_lshr_b32 s3, s33, 3
	s_bfm_b64 s[8:9], s3, 0
	s_cmpk_gt_u32 s33, 0x1ff
	s_cselect_b64 s[8:9], -1, s[8:9]
	s_mov_b64 exec, -1
	v_mbcnt_lo_u32_b32 v229, -1, 0
	v_mbcnt_hi_u32_b32 v229, -1, v229
	v_lshlrev_b32_e32 v229, 4, v229
	s_mov_b32 s10, 0x930c930c
	s_mov_b64 exec, s[8:9]

.Lgbar_rel_11:
	s_mov_b64 exec, -1
	v_lshlrev_b32_e32 v0, 4, v229
	v_mov_b32_e32 v1, 0x93a7000c
	s_mov_b32 exec_lo, 0xff
	s_mov_b32 exec_hi, 0
	global_store_dword v0, v1, s[4:5] offset:1024 sc1
	s_mov_b64 exec, 1

.Lgbar_spin_11:
	global_load_dword v1, v0, s[4:5] offset:1024 sc1
	s_waitcnt vmcnt(0)
	v_cmp_eq_u32_e32 vcc, 0x93a7000c, v1
	s_cbranch_vccnz .Lgbar_done_11
	s_sleep 1
	s_branch .Lgbar_spin_11

.LBB0_1102:
	s_cmp_gt_i32 s17, 13
	s_cselect_b64 s[6:7], -1, 0
	s_and_b64 s[0:1], s[0:1], s[6:7]
	s_andn2_b64 vcc, exec, s[0:1]
	s_cbranch_vccnz .LBB0_1114
	s_waitcnt vmcnt(0)
	v_or_b32_e32 v0, v201, v200
	s_movk_i32 s0, 0x3ff
	v_and_or_b32 v0, v0, s0, v199
	v_cmp_eq_u32_e32 vcc, 0, v0
	s_waitcnt lgkmcnt(0)
	s_barrier
	s_and_saveexec_b64 s[0:1], vcc
	s_cbranch_execz .LBB0_1113
	buffer_wbl2 sc1
	s_waitcnt vmcnt(0)
	s_add_u32 s4, s14, 0x5be8c00
	s_addc_u32 s5, s15, 0
	s_lshl_b32 s3, s2, 1
	v_mov_b32_e32 v0, s3
	v_mov_b32_e32 v1, 0x930d
	global_store_short v0, v1, s[4:5] sc1
	s_cmp_lg_u32 s2, 0
	s_cbranch_scc1 .Lgbar_wait_12
	s_lshr_b32 s3, s33, 3
	s_bfm_b64 s[8:9], s3, 0
	s_cmpk_gt_u32 s33, 0x1ff
	s_cselect_b64 s[8:9], -1, s[8:9]
	s_mov_b64 exec, -1
	v_mbcnt_lo_u32_b32 v229, -1, 0
	v_mbcnt_hi_u32_b32 v229, -1, v229
	v_lshlrev_b32_e32 v229, 4, v229
	s_mov_b32 s10, 0x930d930d
	s_mov_b64 exec, s[8:9]

.Lgbar_rel_12:
	s_mov_b64 exec, -1
	v_lshlrev_b32_e32 v0, 4, v229
	v_mov_b32_e32 v1, 0x93a7000d
	s_mov_b32 exec_lo, 0xff
	s_mov_b32 exec_hi, 0
	global_store_dword v0, v1, s[4:5] offset:1024 sc1
	s_mov_b64 exec, 1

.Lgbar_spin_12:
	global_load_dword v1, v0, s[4:5] offset:1024 sc1
	s_waitcnt vmcnt(0)
	v_cmp_eq_u32_e32 vcc, 0x93a7000d, v1
	s_cbranch_vccnz .Lgbar_done_12
	s_sleep 1
	s_branch .Lgbar_spin_12

.LBB0_1154:
	s_cmp_gt_i32 s17, 14
	s_cselect_b64 s[0:1], -1, 0
	s_and_b64 s[4:5], s[4:5], s[0:1]
	s_andn2_b64 vcc, exec, s[4:5]
	s_cbranch_vccnz .LBB0_1166
	s_waitcnt vmcnt(0)
	v_or_b32_e32 v0, v201, v200
	s_movk_i32 s3, 0x3ff
	v_and_or_b32 v0, v0, s3, v199
	v_cmp_eq_u32_e32 vcc, 0, v0
	s_waitcnt lgkmcnt(0)
	s_barrier
	s_and_saveexec_b64 s[4:5], vcc
	s_cbranch_execz .LBB0_1165
	buffer_wbl2 sc1
	s_waitcnt vmcnt(0)
	s_add_u32 s6, s14, 0x5be8c00
	s_addc_u32 s7, s15, 0
	s_lshl_b32 s3, s2, 1
	v_mov_b32_e32 v0, s3
	v_mov_b32_e32 v1, 0x930e
	global_store_short v0, v1, s[6:7] sc1
	s_cmp_lg_u32 s2, 0
	s_cbranch_scc1 .Lgbar_wait_13
	s_lshr_b32 s3, s33, 3
	s_bfm_b64 s[8:9], s3, 0
	s_cmpk_gt_u32 s33, 0x1ff
	s_cselect_b64 s[8:9], -1, s[8:9]
	s_mov_b64 exec, -1
	v_mbcnt_lo_u32_b32 v229, -1, 0
	v_mbcnt_hi_u32_b32 v229, -1, v229
	v_lshlrev_b32_e32 v229, 4, v229
	s_mov_b32 s10, 0x930e930e
	s_mov_b64 exec, s[8:9]

.Lgbar_rel_13:
	s_mov_b64 exec, -1
	v_lshlrev_b32_e32 v0, 4, v229
	v_mov_b32_e32 v1, 0x93a7000e
	s_mov_b32 exec_lo, 0xff
	s_mov_b32 exec_hi, 0
	global_store_dword v0, v1, s[6:7] offset:1024 sc1
	s_mov_b64 exec, 1

.Lgbar_spin_13:
	global_load_dword v1, v0, s[6:7] offset:1024 sc1
	s_waitcnt vmcnt(0)
	v_cmp_eq_u32_e32 vcc, 0x93a7000e, v1
	s_cbranch_vccnz .Lgbar_done_13
	s_sleep 1
	s_branch .Lgbar_spin_13

.LBB0_1270:
	s_cmp_gt_i32 s17, 15
	s_cselect_b64 s[4:5], -1, 0
	s_and_b64 s[0:1], s[6:7], s[4:5]
	s_andn2_b64 vcc, exec, s[0:1]
	s_cbranch_vccnz .LBB0_1282
	s_waitcnt vmcnt(0)
	v_or_b32_e32 v0, v201, v200
	s_movk_i32 s0, 0x3ff
	v_and_or_b32 v0, v0, s0, v199
	v_cmp_eq_u32_e32 vcc, 0, v0
	s_waitcnt lgkmcnt(0)
	s_barrier
	s_and_saveexec_b64 s[0:1], vcc
	s_cbranch_execz .LBB0_1281
	buffer_wbl2 sc1
	s_waitcnt vmcnt(0)
	s_add_u32 s6, s14, 0x5be8c00
	s_addc_u32 s7, s15, 0
	s_lshl_b32 s3, s2, 1
	v_mov_b32_e32 v0, s3
	v_mov_b32_e32 v1, 0x930f
	global_store_short v0, v1, s[6:7] sc1
	s_cmp_lg_u32 s2, 0
	s_cbranch_scc1 .Lgbar_wait_14
	s_lshr_b32 s3, s33, 3
	s_bfm_b64 s[8:9], s3, 0
	s_cmpk_gt_u32 s33, 0x1ff
	s_cselect_b64 s[8:9], -1, s[8:9]
	s_mov_b64 exec, -1
	v_mbcnt_lo_u32_b32 v229, -1, 0
	v_mbcnt_hi_u32_b32 v229, -1, v229
	v_lshlrev_b32_e32 v229, 4, v229
	s_mov_b32 s10, 0x930f930f
	s_mov_b64 exec, s[8:9]

.Lgbar_rel_14:
	s_mov_b64 exec, -1
	v_lshlrev_b32_e32 v0, 4, v229
	v_mov_b32_e32 v1, 0x93a7000f
	s_mov_b32 exec_lo, 0xff
	s_mov_b32 exec_hi, 0
	global_store_dword v0, v1, s[6:7] offset:1024 sc1
	s_mov_b64 exec, 1

.Lgbar_spin_14:
	global_load_dword v1, v0, s[6:7] offset:1024 sc1
	s_waitcnt vmcnt(0)
	v_cmp_eq_u32_e32 vcc, 0x93a7000f, v1
	s_cbranch_vccnz .Lgbar_done_14
	s_sleep 1
	s_branch .Lgbar_spin_14

.LBB0_1306:
	s_cmp_gt_i32 s17, 16
	s_cselect_b64 s[6:7], -1, 0
	s_and_b64 s[0:1], s[0:1], s[6:7]
	s_andn2_b64 vcc, exec, s[0:1]
	s_cbranch_vccnz .LBB0_1318
	s_waitcnt vmcnt(0)
	v_or_b32_e32 v0, v201, v200
	s_movk_i32 s0, 0x3ff
	v_and_or_b32 v0, v0, s0, v199
	v_cmp_eq_u32_e32 vcc, 0, v0
	s_waitcnt lgkmcnt(0)
	s_barrier
	s_and_saveexec_b64 s[0:1], vcc
	s_cbranch_execz .LBB0_1317
	buffer_wbl2 sc1
	s_waitcnt vmcnt(0)
	s_add_u32 s4, s14, 0x5be8c00
	s_addc_u32 s5, s15, 0
	s_lshl_b32 s3, s2, 1
	v_mov_b32_e32 v0, s3
	v_mov_b32_e32 v1, 0x9310
	global_store_short v0, v1, s[4:5] sc1
	s_cmp_lg_u32 s2, 0
	s_cbranch_scc1 .Lgbar_wait_15
	s_lshr_b32 s3, s33, 3
	s_bfm_b64 s[8:9], s3, 0
	s_cmpk_gt_u32 s33, 0x1ff
	s_cselect_b64 s[8:9], -1, s[8:9]
	s_mov_b64 exec, -1
	v_mbcnt_lo_u32_b32 v229, -1, 0
	v_mbcnt_hi_u32_b32 v229, -1, v229
	v_lshlrev_b32_e32 v229, 4, v229
	s_mov_b32 s10, 0x93109310
	s_mov_b64 exec, s[8:9]

.Lgbar_rel_15:
	s_mov_b64 exec, -1
	v_lshlrev_b32_e32 v0, 4, v229
	v_mov_b32_e32 v1, 0x93a70010
	s_mov_b32 exec_lo, 0xff
	s_mov_b32 exec_hi, 0
	global_store_dword v0, v1, s[4:5] offset:1024 sc1
	s_mov_b64 exec, 1

.Lgbar_spin_15:
	global_load_dword v1, v0, s[4:5] offset:1024 sc1
	s_waitcnt vmcnt(0)
	v_cmp_eq_u32_e32 vcc, 0x93a70010, v1
	s_cbranch_vccnz .Lgbar_done_15
	s_sleep 1
	s_branch .Lgbar_spin_15

.LBB0_1358:
	s_cmp_gt_i32 s17, 17
	s_cselect_b64 s[6:7], -1, 0
	s_and_b64 s[0:1], s[4:5], s[6:7]
	s_andn2_b64 vcc, exec, s[0:1]
	s_cbranch_vccnz .LBB0_1370
	s_waitcnt vmcnt(0)
	v_or_b32_e32 v0, v201, v200
	s_movk_i32 s0, 0x3ff
	v_and_or_b32 v0, v0, s0, v199
	v_cmp_eq_u32_e32 vcc, 0, v0
	s_waitcnt lgkmcnt(0)
	s_barrier
	s_and_saveexec_b64 s[0:1], vcc
	s_cbranch_execz .LBB0_1369
	buffer_wbl2 sc1
	s_waitcnt vmcnt(0)
	s_add_u32 s4, s14, 0x5be8c00
	s_addc_u32 s5, s15, 0
	s_lshl_b32 s3, s2, 1
	v_mov_b32_e32 v0, s3
	v_mov_b32_e32 v1, 0x9311
	global_store_short v0, v1, s[4:5] sc1
	s_cmp_lg_u32 s2, 0
	s_cbranch_scc1 .Lgbar_wait_16
	s_lshr_b32 s3, s33, 3
	s_bfm_b64 s[8:9], s3, 0
	s_cmpk_gt_u32 s33, 0x1ff
	s_cselect_b64 s[8:9], -1, s[8:9]
	s_mov_b64 exec, -1
	v_mbcnt_lo_u32_b32 v229, -1, 0
	v_mbcnt_hi_u32_b32 v229, -1, v229
	v_lshlrev_b32_e32 v229, 4, v229
	s_mov_b32 s10, 0x93119311
	s_mov_b64 exec, s[8:9]

.Lgbar_rel_16:
	s_mov_b64 exec, -1
	v_lshlrev_b32_e32 v0, 4, v229
	v_mov_b32_e32 v1, 0x93a70011
	s_mov_b32 exec_lo, 0xff
	s_mov_b32 exec_hi, 0
	global_store_dword v0, v1, s[4:5] offset:1024 sc1
	s_mov_b64 exec, 1

.Lgbar_spin_16:
	global_load_dword v1, v0, s[4:5] offset:1024 sc1
	s_waitcnt vmcnt(0)
	v_cmp_eq_u32_e32 vcc, 0x93a70011, v1
	s_cbranch_vccnz .Lgbar_done_16
	s_sleep 1
	s_branch .Lgbar_spin_16

.LBB0_1378:
	s_cmp_gt_i32 s17, 18
	s_cselect_b64 s[6:7], -1, 0
	s_and_b64 s[0:1], s[0:1], s[6:7]
	s_andn2_b64 vcc, exec, s[0:1]
	s_cbranch_vccnz .LBB0_1390
	s_waitcnt vmcnt(0)
	v_or_b32_e32 v0, v201, v200
	s_movk_i32 s0, 0x3ff
	v_and_or_b32 v0, v0, s0, v199
	v_cmp_eq_u32_e32 vcc, 0, v0
	s_waitcnt lgkmcnt(0)
	s_barrier
	s_and_saveexec_b64 s[0:1], vcc
	s_cbranch_execz .LBB0_1389
	buffer_wbl2 sc1
	s_waitcnt vmcnt(0)
	s_add_u32 s4, s14, 0x5be8c00
	s_addc_u32 s5, s15, 0
	s_lshl_b32 s3, s2, 1
	v_mov_b32_e32 v0, s3
	v_mov_b32_e32 v1, 0x9312
	global_store_short v0, v1, s[4:5] sc1
	s_cmp_lg_u32 s2, 0
	s_cbranch_scc1 .Lgbar_wait_17
	s_lshr_b32 s3, s33, 3
	s_bfm_b64 s[8:9], s3, 0
	s_cmpk_gt_u32 s33, 0x1ff
	s_cselect_b64 s[8:9], -1, s[8:9]
	s_mov_b64 exec, -1
	v_mbcnt_lo_u32_b32 v229, -1, 0
	v_mbcnt_hi_u32_b32 v229, -1, v229
	v_lshlrev_b32_e32 v229, 4, v229
	s_mov_b32 s10, 0x93129312
	s_mov_b64 exec, s[8:9]

.Lgbar_rel_17:
	s_mov_b64 exec, -1
	v_lshlrev_b32_e32 v0, 4, v229
	v_mov_b32_e32 v1, 0x93a70012
	s_mov_b32 exec_lo, 0xff
	s_mov_b32 exec_hi, 0
	global_store_dword v0, v1, s[4:5] offset:1024 sc1
	s_mov_b64 exec, 1

.Lgbar_spin_17:
	global_load_dword v1, v0, s[4:5] offset:1024 sc1
	s_waitcnt vmcnt(0)
	v_cmp_eq_u32_e32 vcc, 0x93a70012, v1
	s_cbranch_vccnz .Lgbar_done_17
	s_sleep 1
	s_branch .Lgbar_spin_17

.LBB0_1430:
	s_cmp_gt_i32 s17, 19
	s_cselect_b64 s[6:7], -1, 0
	s_and_b64 s[0:1], s[4:5], s[6:7]
	s_andn2_b64 vcc, exec, s[0:1]
	s_cbranch_vccnz .LBB0_1442
	s_waitcnt vmcnt(0)
	v_or_b32_e32 v0, v201, v200
	s_movk_i32 s0, 0x3ff
	v_and_or_b32 v0, v0, s0, v199
	v_cmp_eq_u32_e32 vcc, 0, v0
	s_waitcnt lgkmcnt(0)
	s_barrier
	s_and_saveexec_b64 s[0:1], vcc
	s_cbranch_execz .LBB0_1441
	buffer_wbl2 sc1
	s_waitcnt vmcnt(0)
	s_add_u32 s4, s14, 0x5be8c00
	s_addc_u32 s5, s15, 0
	s_lshl_b32 s3, s2, 1
	v_mov_b32_e32 v0, s3
	v_mov_b32_e32 v1, 0x9313
	global_store_short v0, v1, s[4:5] sc1
	s_cmp_lg_u32 s2, 0
	s_cbranch_scc1 .Lgbar_wait_18
	s_lshr_b32 s3, s33, 3
	s_bfm_b64 s[8:9], s3, 0
	s_cmpk_gt_u32 s33, 0x1ff
	s_cselect_b64 s[8:9], -1, s[8:9]
	s_mov_b64 exec, -1
	v_mbcnt_lo_u32_b32 v229, -1, 0
	v_mbcnt_hi_u32_b32 v229, -1, v229
	v_lshlrev_b32_e32 v229, 4, v229
	s_mov_b32 s10, 0x93139313
	s_mov_b64 exec, s[8:9]

.Lgbar_rel_18:
	s_mov_b64 exec, -1
	v_lshlrev_b32_e32 v0, 4, v229
	v_mov_b32_e32 v1, 0x93a70013
	s_mov_b32 exec_lo, 0xff
	s_mov_b32 exec_hi, 0
	global_store_dword v0, v1, s[4:5] offset:1024 sc1
	s_mov_b64 exec, 1

.Lgbar_spin_18:
	global_load_dword v1, v0, s[4:5] offset:1024 sc1
	s_waitcnt vmcnt(0)
	v_cmp_eq_u32_e32 vcc, 0x93a70013, v1
	s_cbranch_vccnz .Lgbar_done_18
	s_sleep 1
	s_branch .Lgbar_spin_18

.LBB0_1454:
	s_cmp_gt_i32 s17, 20
	s_cselect_b64 s[4:5], -1, 0
	s_and_b64 s[0:1], s[0:1], s[4:5]
	s_andn2_b64 vcc, exec, s[0:1]
	s_cbranch_vccnz .LBB0_1466
	s_waitcnt vmcnt(0)
	v_or_b32_e32 v0, v201, v200
	s_movk_i32 s0, 0x3ff
	v_and_or_b32 v0, v0, s0, v199
	v_cmp_eq_u32_e32 vcc, 0, v0
	s_waitcnt lgkmcnt(0)
	s_barrier
	s_and_saveexec_b64 s[0:1], vcc
	s_cbranch_execz .LBB0_1465
	buffer_wbl2 sc1
	s_waitcnt vmcnt(0)
	s_add_u32 s6, s14, 0x5be8c00
	s_addc_u32 s7, s15, 0
	s_lshl_b32 s3, s2, 1
	v_mov_b32_e32 v0, s3
	v_mov_b32_e32 v1, 0x9314
	global_store_short v0, v1, s[6:7] sc1
	s_cmp_lg_u32 s2, 0
	s_cbranch_scc1 .Lgbar_wait_19
	s_lshr_b32 s3, s33, 3
	s_bfm_b64 s[8:9], s3, 0
	s_cmpk_gt_u32 s33, 0x1ff
	s_cselect_b64 s[8:9], -1, s[8:9]
	s_mov_b64 exec, -1
	v_mbcnt_lo_u32_b32 v229, -1, 0
	v_mbcnt_hi_u32_b32 v229, -1, v229
	v_lshlrev_b32_e32 v229, 4, v229
	s_mov_b32 s10, 0x93149314
	s_mov_b64 exec, s[8:9]

.Lgbar_rel_19:
	s_mov_b64 exec, -1
	v_lshlrev_b32_e32 v0, 4, v229
	v_mov_b32_e32 v1, 0x93a70014
	s_mov_b32 exec_lo, 0xff
	s_mov_b32 exec_hi, 0
	global_store_dword v0, v1, s[6:7] offset:1024 sc1
	s_mov_b64 exec, 1

.Lgbar_spin_19:
	global_load_dword v1, v0, s[6:7] offset:1024 sc1
	s_waitcnt vmcnt(0)
	v_cmp_eq_u32_e32 vcc, 0x93a70014, v1
	s_cbranch_vccnz .Lgbar_done_19
	s_sleep 1
	s_branch .Lgbar_spin_19

.LBB0_1479:
	s_cmp_gt_i32 s17, 21
	s_cselect_b64 s[4:5], -1, 0
	s_and_b64 s[0:1], s[0:1], s[4:5]
	s_andn2_b64 vcc, exec, s[0:1]
	s_cbranch_vccnz .LBB0_1491
	s_waitcnt vmcnt(0)
	v_or_b32_e32 v0, v201, v200
	s_movk_i32 s0, 0x3ff
	v_and_or_b32 v0, v0, s0, v199
	v_cmp_eq_u32_e32 vcc, 0, v0
	s_waitcnt lgkmcnt(0)
	s_barrier
	s_and_saveexec_b64 s[0:1], vcc
	s_cbranch_execz .LBB0_1490
	buffer_wbl2 sc1
	s_waitcnt vmcnt(0)
	s_add_u32 s6, s14, 0x5be8c00
	s_addc_u32 s7, s15, 0
	s_lshl_b32 s3, s2, 1
	v_mov_b32_e32 v0, s3
	v_mov_b32_e32 v1, 0x9315
	global_store_short v0, v1, s[6:7] sc1
	s_cmp_lg_u32 s2, 0
	s_cbranch_scc1 .Lgbar_wait_20
	s_lshr_b32 s3, s33, 3
	s_bfm_b64 s[8:9], s3, 0
	s_cmpk_gt_u32 s33, 0x1ff
	s_cselect_b64 s[8:9], -1, s[8:9]
	s_mov_b64 exec, -1
	v_mbcnt_lo_u32_b32 v229, -1, 0
	v_mbcnt_hi_u32_b32 v229, -1, v229
	v_lshlrev_b32_e32 v229, 4, v229
	s_mov_b32 s10, 0x93159315
	s_mov_b64 exec, s[8:9]

.Lgbar_rel_20:
	s_mov_b64 exec, -1
	v_lshlrev_b32_e32 v0, 4, v229
	v_mov_b32_e32 v1, 0x93a70015
	s_mov_b32 exec_lo, 0xff
	s_mov_b32 exec_hi, 0
	global_store_dword v0, v1, s[6:7] offset:1024 sc1
	s_mov_b64 exec, 1

.Lgbar_spin_20:
	global_load_dword v1, v0, s[6:7] offset:1024 sc1
	s_waitcnt vmcnt(0)
	v_cmp_eq_u32_e32 vcc, 0x93a70015, v1
	s_cbranch_vccnz .Lgbar_done_20
	s_sleep 1
	s_branch .Lgbar_spin_20

.LBB0_1495:
	s_cmp_gt_i32 s17, 22
	s_cselect_b64 s[4:5], -1, 0
	s_and_b64 s[0:1], s[6:7], s[4:5]
	s_andn2_b64 vcc, exec, s[0:1]
	s_cbranch_vccnz .LBB0_1507
	s_waitcnt vmcnt(0)
	v_or_b32_e32 v0, v201, v200
	s_movk_i32 s0, 0x3ff
	v_and_or_b32 v0, v0, s0, v199
	v_cmp_eq_u32_e32 vcc, 0, v0
	s_waitcnt lgkmcnt(0)
	s_barrier
	s_and_saveexec_b64 s[0:1], vcc
	s_cbranch_execz .LBB0_1506
	buffer_wbl2 sc1
	s_waitcnt vmcnt(0)
	s_add_u32 s6, s14, 0x5be8c00
	s_addc_u32 s7, s15, 0
	s_lshl_b32 s3, s2, 1
	v_mov_b32_e32 v0, s3
	v_mov_b32_e32 v1, 0x9316
	global_store_short v0, v1, s[6:7] sc1
	s_cmp_lg_u32 s2, 0
	s_cbranch_scc1 .Lgbar_wait_21
	s_lshr_b32 s3, s33, 3
	s_bfm_b64 s[8:9], s3, 0
	s_cmpk_gt_u32 s33, 0x1ff
	s_cselect_b64 s[8:9], -1, s[8:9]
	s_mov_b64 exec, -1
	v_mbcnt_lo_u32_b32 v229, -1, 0
	v_mbcnt_hi_u32_b32 v229, -1, v229
	v_lshlrev_b32_e32 v229, 4, v229
	s_mov_b32 s10, 0x93169316
	s_mov_b64 exec, s[8:9]

.Lgbar_rel_21:
	s_mov_b64 exec, -1
	v_lshlrev_b32_e32 v0, 4, v229
	v_mov_b32_e32 v1, 0x93a70016
	s_mov_b32 exec_lo, 0xff
	s_mov_b32 exec_hi, 0
	global_store_dword v0, v1, s[6:7] offset:1024 sc1
	s_mov_b64 exec, 1

.Lgbar_spin_21:
	global_load_dword v1, v0, s[6:7] offset:1024 sc1
	s_waitcnt vmcnt(0)
	v_cmp_eq_u32_e32 vcc, 0x93a70016, v1
	s_cbranch_vccnz .Lgbar_done_21
	s_sleep 1
	s_branch .Lgbar_spin_21

.LBB0_1513:
	s_cmp_gt_i32 s17, 23
	s_cselect_b64 s[6:7], -1, 0
	s_and_b64 s[0:1], s[0:1], s[6:7]
	s_andn2_b64 vcc, exec, s[0:1]
	s_cbranch_vccnz .LBB0_1525
	s_waitcnt vmcnt(0)
	v_or_b32_e32 v0, v201, v200
	s_movk_i32 s0, 0x3ff
	v_and_or_b32 v0, v0, s0, v199
	v_cmp_eq_u32_e32 vcc, 0, v0
	s_waitcnt lgkmcnt(0)
	s_barrier
	s_and_saveexec_b64 s[0:1], vcc
	s_cbranch_execz .LBB0_1524
	buffer_wbl2 sc1
	s_waitcnt vmcnt(0)
	s_add_u32 s4, s14, 0x5be8c00
	s_addc_u32 s5, s15, 0
	s_lshl_b32 s3, s2, 1
	v_mov_b32_e32 v0, s3
	v_mov_b32_e32 v1, 0x9317
	global_store_short v0, v1, s[4:5] sc1
	s_cmp_lg_u32 s2, 0
	s_cbranch_scc1 .Lgbar_wait_22
	s_lshr_b32 s3, s33, 3
	s_bfm_b64 s[8:9], s3, 0
	s_cmpk_gt_u32 s33, 0x1ff
	s_cselect_b64 s[8:9], -1, s[8:9]
	s_mov_b64 exec, -1
	v_mbcnt_lo_u32_b32 v229, -1, 0
	v_mbcnt_hi_u32_b32 v229, -1, v229
	v_lshlrev_b32_e32 v229, 4, v229
	s_mov_b32 s10, 0x93179317
	s_mov_b64 exec, s[8:9]

.Lgbar_rel_22:
	s_mov_b64 exec, -1
	v_lshlrev_b32_e32 v0, 4, v229
	v_mov_b32_e32 v1, 0x93a70017
	s_mov_b32 exec_lo, 0xff
	s_mov_b32 exec_hi, 0
	global_store_dword v0, v1, s[4:5] offset:1024 sc1
	s_mov_b64 exec, 1

.Lgbar_spin_22:
	global_load_dword v1, v0, s[4:5] offset:1024 sc1
	s_waitcnt vmcnt(0)
	v_cmp_eq_u32_e32 vcc, 0x93a70017, v1
	s_cbranch_vccnz .Lgbar_done_22
	s_sleep 1
	s_branch .Lgbar_spin_22

.LBB0_1549:
	s_cmp_gt_i32 s17, 24
	s_cselect_b64 s[0:1], -1, 0
	s_and_b64 s[4:5], s[4:5], s[0:1]
	s_andn2_b64 vcc, exec, s[4:5]
	s_cbranch_vccnz .LBB0_1561
	s_waitcnt vmcnt(0)
	v_or_b32_e32 v0, v201, v200
	s_movk_i32 s3, 0x3ff
	v_and_or_b32 v0, v0, s3, v199
	v_cmp_eq_u32_e32 vcc, 0, v0
	s_waitcnt lgkmcnt(0)
	s_barrier
	s_and_saveexec_b64 s[4:5], vcc
	s_cbranch_execz .LBB0_1560
	buffer_wbl2 sc1
	s_waitcnt vmcnt(0)
	s_add_u32 s6, s14, 0x5be8c00
	s_addc_u32 s7, s15, 0
	s_lshl_b32 s3, s2, 1
	v_mov_b32_e32 v0, s3
	v_mov_b32_e32 v1, 0x9318
	global_store_short v0, v1, s[6:7] sc1
	s_cmp_lg_u32 s2, 0
	s_cbranch_scc1 .Lgbar_wait_23
	s_lshr_b32 s3, s33, 3
	s_bfm_b64 s[8:9], s3, 0
	s_cmpk_gt_u32 s33, 0x1ff
	s_cselect_b64 s[8:9], -1, s[8:9]
	s_mov_b64 exec, -1
	v_mbcnt_lo_u32_b32 v229, -1, 0
	v_mbcnt_hi_u32_b32 v229, -1, v229
	v_lshlrev_b32_e32 v229, 4, v229
	s_mov_b32 s10, 0x93189318
	s_mov_b64 exec, s[8:9]

.Lgbar_rel_23:
	s_mov_b64 exec, -1
	v_lshlrev_b32_e32 v0, 4, v229
	v_mov_b32_e32 v1, 0x93a70018
	s_mov_b32 exec_lo, 0xff
	s_mov_b32 exec_hi, 0
	global_store_dword v0, v1, s[6:7] offset:1024 sc1
	s_mov_b64 exec, 1

.Lgbar_spin_23:
	global_load_dword v1, v0, s[6:7] offset:1024 sc1
	s_waitcnt vmcnt(0)
	v_cmp_eq_u32_e32 vcc, 0x93a70018, v1
	s_cbranch_vccnz .Lgbar_done_23
	s_sleep 1
	s_branch .Lgbar_spin_23

.LBB0_1601:
	s_cmp_gt_i32 s17, 25
	s_cselect_b64 s[6:7], -1, 0
	s_and_b64 s[0:1], s[4:5], s[6:7]
	s_andn2_b64 vcc, exec, s[0:1]
	s_cbranch_vccnz .LBB0_1613
	s_waitcnt vmcnt(0)
	v_or_b32_e32 v0, v201, v200
	s_movk_i32 s0, 0x3ff
	v_and_or_b32 v0, v0, s0, v199
	v_cmp_eq_u32_e32 vcc, 0, v0
	s_waitcnt lgkmcnt(0)
	s_barrier
	s_and_saveexec_b64 s[0:1], vcc
	s_cbranch_execz .LBB0_1612
	buffer_wbl2 sc1
	s_waitcnt vmcnt(0)
	s_add_u32 s4, s14, 0x5be8c00
	s_addc_u32 s5, s15, 0
	s_lshl_b32 s3, s2, 1
	v_mov_b32_e32 v0, s3
	v_mov_b32_e32 v1, 0x9319
	global_store_short v0, v1, s[4:5] sc1
	s_cmp_lg_u32 s2, 0
	s_cbranch_scc1 .Lgbar_wait_24
	s_lshr_b32 s3, s33, 3
	s_bfm_b64 s[8:9], s3, 0
	s_cmpk_gt_u32 s33, 0x1ff
	s_cselect_b64 s[8:9], -1, s[8:9]
	s_mov_b64 exec, -1
	v_mbcnt_lo_u32_b32 v229, -1, 0
	v_mbcnt_hi_u32_b32 v229, -1, v229
	v_lshlrev_b32_e32 v229, 4, v229
	s_mov_b32 s10, 0x93199319
	s_mov_b64 exec, s[8:9]

.Lgbar_rel_24:
	s_mov_b64 exec, -1
	v_lshlrev_b32_e32 v0, 4, v229
	v_mov_b32_e32 v1, 0x93a70019
	s_mov_b32 exec_lo, 0xff
	s_mov_b32 exec_hi, 0
	global_store_dword v0, v1, s[4:5] offset:1024 sc1
	s_mov_b64 exec, 1

.Lgbar_spin_24:
	global_load_dword v1, v0, s[4:5] offset:1024 sc1
	s_waitcnt vmcnt(0)
	v_cmp_eq_u32_e32 vcc, 0x93a70019, v1
	s_cbranch_vccnz .Lgbar_done_24
	s_sleep 1
	s_branch .Lgbar_spin_24

.LBB0_1621:
	s_cmp_gt_i32 s17, 26
	s_cselect_b64 s[4:5], -1, 0
	s_and_b64 s[0:1], s[0:1], s[4:5]
	s_andn2_b64 vcc, exec, s[0:1]
	s_cbranch_vccnz .LBB0_1633
	s_waitcnt vmcnt(0)
	v_or_b32_e32 v0, v201, v200
	s_movk_i32 s0, 0x3ff
	v_and_or_b32 v0, v0, s0, v199
	v_cmp_eq_u32_e32 vcc, 0, v0
	s_waitcnt lgkmcnt(0)
	s_barrier
	s_and_saveexec_b64 s[0:1], vcc
	s_cbranch_execz .LBB0_1632
	buffer_wbl2 sc1
	s_waitcnt vmcnt(0)
	s_add_u32 s6, s14, 0x5be8c00
	s_addc_u32 s7, s15, 0
	s_lshl_b32 s3, s2, 1
	v_mov_b32_e32 v0, s3
	v_mov_b32_e32 v1, 0x931a
	global_store_short v0, v1, s[6:7] sc1
	s_cmp_lg_u32 s2, 0
	s_cbranch_scc1 .Lgbar_wait_25
	s_lshr_b32 s3, s33, 3
	s_bfm_b64 s[8:9], s3, 0
	s_cmpk_gt_u32 s33, 0x1ff
	s_cselect_b64 s[8:9], -1, s[8:9]
	s_mov_b64 exec, -1
	v_mbcnt_lo_u32_b32 v229, -1, 0
	v_mbcnt_hi_u32_b32 v229, -1, v229
	v_lshlrev_b32_e32 v229, 4, v229
	s_mov_b32 s10, 0x931a931a
	s_mov_b64 exec, s[8:9]

.Lgbar_rel_25:
	s_mov_b64 exec, -1
	v_lshlrev_b32_e32 v0, 4, v229
	v_mov_b32_e32 v1, 0x93a7001a
	s_mov_b32 exec_lo, 0xff
	s_mov_b32 exec_hi, 0
	global_store_dword v0, v1, s[6:7] offset:1024 sc1
	s_mov_b64 exec, 1

.Lgbar_spin_25:
	global_load_dword v1, v0, s[6:7] offset:1024 sc1
	s_waitcnt vmcnt(0)
	v_cmp_eq_u32_e32 vcc, 0x93a7001a, v1
	s_cbranch_vccnz .Lgbar_done_25
	s_sleep 1
	s_branch .Lgbar_spin_25

	.amdhsa_kernel _Z4mega5KArgs
		.amdhsa_group_segment_fixed_size 0
		.amdhsa_private_segment_fixed_size 0
		.amdhsa_kernarg_size 592
		.amdhsa_user_sgpr_count 2
		.amdhsa_user_sgpr_dispatch_ptr 0
		.amdhsa_user_sgpr_queue_ptr 0
		.amdhsa_user_sgpr_kernarg_segment_ptr 1
		.amdhsa_user_sgpr_dispatch_id 0
		.amdhsa_user_sgpr_kernarg_preload_length 0
		.amdhsa_user_sgpr_kernarg_preload_offset 0
		.amdhsa_user_sgpr_private_segment_size 0
		.amdhsa_uses_dynamic_stack 0
		.amdhsa_enable_private_segment 0
		.amdhsa_system_sgpr_workgroup_id_x 1
		.amdhsa_system_sgpr_workgroup_id_y 0
		.amdhsa_system_sgpr_workgroup_id_z 0
		.amdhsa_system_sgpr_workgroup_info 0
		.amdhsa_system_vgpr_workitem_id 2
		.amdhsa_next_free_vgpr 232
		.amdhsa_next_free_sgpr 98
		.amdhsa_accum_offset 232
		.amdhsa_reserve_vcc 1
		.amdhsa_float_round_mode_32 0
		.amdhsa_float_round_mode_16_64 0
		.amdhsa_float_denorm_mode_32 3
		.amdhsa_float_denorm_mode_16_64 3
		.amdhsa_dx10_clamp 1
		.amdhsa_ieee_mode 1
		.amdhsa_fp16_overflow 0
		.amdhsa_tg_split 0
		.amdhsa_exception_fp_ieee_invalid_op 0
		.amdhsa_exception_fp_denorm_src 0
		.amdhsa_exception_fp_ieee_div_zero 0
		.amdhsa_exception_fp_ieee_overflow 0
		.amdhsa_exception_fp_ieee_underflow 0
		.amdhsa_exception_fp_ieee_inexact 0
		.amdhsa_exception_int_div_zero 0
	.end_amdhsa_kernel

amdhsa.kernels:
  - .agpr_count:     0
    .args:
      - .offset:         0
        .size:           336
        .value_kind:     by_value
      - .offset:         336
        .size:           4
        .value_kind:     hidden_block_count_x
      - .offset:         340
        .size:           4
        .value_kind:     hidden_block_count_y
      - .offset:         344
        .size:           4
        .value_kind:     hidden_block_count_z
      - .offset:         348
        .size:           2
        .value_kind:     hidden_group_size_x
      - .offset:         350
        .size:           2
        .value_kind:     hidden_group_size_y
      - .offset:         352
        .size:           2
        .value_kind:     hidden_group_size_z
      - .offset:         354
        .size:           2
        .value_kind:     hidden_remainder_x
      - .offset:         356
        .size:           2
        .value_kind:     hidden_remainder_y
      - .offset:         358
        .size:           2
        .value_kind:     hidden_remainder_z
      - .offset:         376
        .size:           8
        .value_kind:     hidden_global_offset_x
      - .offset:         384
        .size:           8
        .value_kind:     hidden_global_offset_y
      - .offset:         392
        .size:           8
        .value_kind:     hidden_global_offset_z
      - .offset:         400
        .size:           2
        .value_kind:     hidden_grid_dims
      - .offset:         424
        .size:           8
        .value_kind:     hidden_multigrid_sync_arg
      - .offset:         456
        .size:           4
        .value_kind:     hidden_dynamic_lds_size
    .group_segment_fixed_size: 0
    .kernarg_segment_align: 8
    .kernarg_segment_size: 592
    .language:       OpenCL C
    .language_version:
      - 2
      - 0
    .max_flat_workgroup_size: 256
    .name:           _Z4mega5KArgs
    .private_segment_fixed_size: 0
    .sgpr_count:     104
    .sgpr_spill_count: 2
    .symbol:         _Z4mega5KArgs.kd
    .uniform_work_group_size: 1
    .uses_dynamic_stack: false
    .vgpr_count:     232
    .vgpr_spill_count: 0
    .wavefront_size: 64
